# v24: + P3 final-epilogue gate loads issued up front (loads-only counted waits), on top of v23
# baseline (speedup 1.0000x reference)
; __device__ __forceinline__ void st8(bf16_t* p, const f32x4& a, const f32x4& b) { u32x4 w; w.x = pk2(a[0], a[1]); w.y = pk2(a[2], a[3]); w.z = pk2(b[0], b[1]); w.w = pk2(b[2], b[3]); *(u32x4*)p = w; }
;     __device__ __forceinline__ void operator()(const f32x4 (&acc)[2][2][4][2], const Unit& u, int wr, int wc, int fr, int fq) const {
;         const int row0 = u.pm * 256 + wr * 64 + fr, col0 = u.pn * 256 + wc * 32 + 8 * fq;
; #pragma unroll
;         for (int ai = 0; ai < 2; ++ai)
; #pragma unroll
;             for (int m = 0; m < 4; ++m) {
;                 const size_t off = (size_t)(row0 + ai * 128 + m * 16) * D + col0;
; #pragma unroll
;                 for (int bj = 0; bj < 2; ++bj) {
;                     const u32x4 g = *(const u32x4*)(GA + off + bj * 128);
;                     st8(O + off + bj * 128, acc[ai][bj][m][0] * (f32x4){bflo(g.x), bfhi(g.x), bflo(g.y), bfhi(g.y)}, acc[ai][bj][m][1] * (f32x4){bflo(g.z), bfhi(g.z), bflo(g.w), bfhi(g.w)});
;                 }
;             }
;     }
.LBB0_569:
	v_ashrrev_i32_e32 v161, 31, v160
	v_lshlrev_b64 v[4:5], 11, v[160:161]
	v_lshl_add_u64 v[4:5], v[4:5], 0, v[158:159]
	v_lshlrev_b64 v[4:5], 1, v[4:5]
	v_mov_b32_e32 v254, v4
	global_load_dwordx4 v[178:181], v254, s[54:55]
	global_load_dwordx4 v[182:185], v254, s[54:55] offset:256
	v_add_u32_e32 v165, 0x10000, v254
	global_load_dwordx4 v[186:189], v165, s[54:55]
	global_load_dwordx4 v[190:193], v165, s[54:55] offset:256
	v_add_u32_e32 v165, 0x20000, v254
	global_load_dwordx4 v[194:197], v165, s[54:55]
	global_load_dwordx4 v[198:201], v165, s[54:55] offset:256
	v_add_u32_e32 v165, 0x30000, v254
	global_load_dwordx4 v[202:205], v165, s[54:55]
	global_load_dwordx4 v[206:209], v165, s[54:55] offset:256
	v_add_u32_e32 v165, 0x80000, v254
	global_load_dwordx4 v[210:213], v165, s[54:55]
	global_load_dwordx4 v[214:217], v165, s[54:55] offset:256
	v_add_u32_e32 v165, 0x90000, v254
	global_load_dwordx4 v[218:221], v165, s[54:55]
	global_load_dwordx4 v[222:225], v165, s[54:55] offset:256
	v_add_u32_e32 v165, 0xa0000, v254
	global_load_dwordx4 v[226:229], v165, s[54:55]
	global_load_dwordx4 v[230:233], v165, s[54:55] offset:256
	v_add_u32_e32 v165, 0xb0000, v254
	global_load_dwordx4 v[234:237], v165, s[54:55]
	global_load_dwordx4 v[238:241], v165, s[54:55] offset:256
	v_lshl_add_u64 v[138:139], s[54:55], 0, v[4:5]
	v_lshl_add_u64 v[140:141], s[30:31], 0, v[4:5]
	s_andn2_b64 vcc, exec, s[2:3]
	s_mov_b64 s[2:3], -1
	s_waitcnt vmcnt(15)
	s_nop 1
	v_mov_b64_e32 v[134:135], v[178:179]
	v_mov_b64_e32 v[136:137], v[180:181]
	v_lshlrev_b32_e32 v166, 16, v134
	v_and_b32_e32 v167, 0xffff0000, v134
	v_lshlrev_b32_e32 v134, 16, v135
	v_and_b32_e32 v135, 0xffff0000, v135
	v_lshlrev_b32_e32 v168, 16, v136
	v_and_b32_e32 v169, 0xffff0000, v136
	v_lshlrev_b32_e32 v136, 16, v137
	v_and_b32_e32 v137, 0xffff0000, v137
	v_pk_mul_f32 v[132:133], v[132:133], v[134:135]
	v_pk_mul_f32 v[134:135], v[128:129], v[136:137]
	v_pk_mul_f32 v[128:129], v[126:127], v[168:169]
	v_pk_mul_f32 v[130:131], v[130:131], v[166:167]
	s_nop 0
	v_cvt_pk_bf16_f32 v126, v130, v131
	v_cvt_pk_bf16_f32 v127, v132, v133
	v_cvt_pk_bf16_f32 v128, v128, v129
	v_cvt_pk_bf16_f32 v129, v134, v135
	global_store_dwordx4 v[140:141], v[126:129], off
	v_or_b32_e32 v130, 16, v160
	v_ashrrev_i32_e32 v131, 31, v130
	v_lshlrev_b64 v[130:131], 11, v[130:131]
	v_lshl_add_u64 v[130:131], v[130:131], 0, v[158:159]
	v_lshlrev_b64 v[130:131], 1, v[130:131]
	v_lshl_add_u64 v[132:133], s[54:55], 0, v[130:131]
	s_waitcnt vmcnt(14)
	s_nop 1
	v_mov_b64_e32 v[126:127], v[182:183]
	v_mov_b64_e32 v[128:129], v[184:185]
	v_lshlrev_b32_e32 v134, 16, v126
	v_and_b32_e32 v135, 0xffff0000, v126
	v_lshlrev_b32_e32 v126, 16, v127
	v_and_b32_e32 v127, 0xffff0000, v127
	v_lshlrev_b32_e32 v136, 16, v128
	v_and_b32_e32 v137, 0xffff0000, v128
	v_lshlrev_b32_e32 v128, 16, v129
	v_and_b32_e32 v129, 0xffff0000, v129
	v_pk_mul_f32 v[124:125], v[124:125], v[126:127]
	v_pk_mul_f32 v[126:127], v[120:121], v[128:129]
	v_pk_mul_f32 v[120:121], v[118:119], v[136:137]
	v_pk_mul_f32 v[122:123], v[122:123], v[134:135]
	s_nop 0
	v_cvt_pk_bf16_f32 v118, v122, v123
	v_cvt_pk_bf16_f32 v119, v124, v125
	v_cvt_pk_bf16_f32 v120, v120, v121
	v_cvt_pk_bf16_f32 v121, v126, v127
	global_store_dwordx4 v[140:141], v[118:121], off offset:256
	v_lshl_add_u64 v[122:123], s[30:31], 0, v[130:131]
	s_waitcnt vmcnt(13)
	s_nop 1
	v_mov_b64_e32 v[118:119], v[186:187]
	v_mov_b64_e32 v[120:121], v[188:189]
	v_lshlrev_b32_e32 v124, 16, v118
	v_and_b32_e32 v125, 0xffff0000, v118
	v_lshlrev_b32_e32 v118, 16, v119
	v_and_b32_e32 v119, 0xffff0000, v119
	v_lshlrev_b32_e32 v126, 16, v120
	v_and_b32_e32 v127, 0xffff0000, v120
	v_lshlrev_b32_e32 v120, 16, v121
	v_and_b32_e32 v121, 0xffff0000, v121
	v_pk_mul_f32 v[116:117], v[116:117], v[118:119]
	v_pk_mul_f32 v[118:119], v[112:113], v[120:121]
	v_pk_mul_f32 v[112:113], v[110:111], v[126:127]
	v_pk_mul_f32 v[114:115], v[114:115], v[124:125]
	s_nop 0
	v_cvt_pk_bf16_f32 v110, v114, v115
	v_cvt_pk_bf16_f32 v111, v116, v117
	v_cvt_pk_bf16_f32 v112, v112, v113
	v_cvt_pk_bf16_f32 v113, v118, v119
	global_store_dwordx4 v[122:123], v[110:113], off
	v_or_b32_e32 v114, 32, v160
	v_ashrrev_i32_e32 v115, 31, v114
	v_lshlrev_b64 v[114:115], 11, v[114:115]
	v_lshl_add_u64 v[114:115], v[114:115], 0, v[158:159]
	v_lshlrev_b64 v[114:115], 1, v[114:115]
	v_lshl_add_u64 v[116:117], s[54:55], 0, v[114:115]
	s_waitcnt vmcnt(12)
	s_nop 1
	v_mov_b64_e32 v[110:111], v[190:191]
	v_mov_b64_e32 v[112:113], v[192:193]
	v_lshlrev_b32_e32 v118, 16, v110
	v_and_b32_e32 v119, 0xffff0000, v110
	v_lshlrev_b32_e32 v110, 16, v111
	v_and_b32_e32 v111, 0xffff0000, v111
	v_lshlrev_b32_e32 v120, 16, v112
	v_and_b32_e32 v121, 0xffff0000, v112
	v_lshlrev_b32_e32 v112, 16, v113
	v_and_b32_e32 v113, 0xffff0000, v113
	v_pk_mul_f32 v[108:109], v[108:109], v[110:111]
	v_pk_mul_f32 v[110:111], v[104:105], v[112:113]
	v_pk_mul_f32 v[104:105], v[102:103], v[120:121]
	v_pk_mul_f32 v[106:107], v[106:107], v[118:119]
	s_nop 0
	v_cvt_pk_bf16_f32 v102, v106, v107
	v_cvt_pk_bf16_f32 v103, v108, v109
	v_cvt_pk_bf16_f32 v104, v104, v105
	v_cvt_pk_bf16_f32 v105, v110, v111
	global_store_dwordx4 v[122:123], v[102:105], off offset:256
	v_lshl_add_u64 v[106:107], s[30:31], 0, v[114:115]
	s_waitcnt vmcnt(11)
; __device__ __forceinline__ void st8(bf16_t* p, const f32x4& a, const f32x4& b) { u32x4 w; w.x = pk2(a[0], a[1]); w.y = pk2(a[2], a[3]); w.z = pk2(b[0], b[1]); w.w = pk2(b[2], b[3]); *(u32x4*)p = w; }
;     __device__ __forceinline__ void operator()(const f32x4 (&acc)[2][2][4][2], const Unit& u, int wr, int wc, int fr, int fq) const {
;     ...
; #pragma unroll
;         for (int ai = 0; ai < 2; ++ai)
; #pragma unroll
;             for (int m = 0; m < 4; ++m) {
;                 const size_t off = (size_t)(row0 + ai * 128 + m * 16) * D + col0;
; #pragma unroll
;                 for (int bj = 0; bj < 2; ++bj) {
;                     const u32x4 g = *(const u32x4*)(GA + off + bj * 128);
;                     st8(O + off + bj * 128, acc[ai][bj][m][0] * (f32x4){bflo(g.x), bfhi(g.x), bflo(g.y), bfhi(g.y)}, acc[ai][bj][m][1] * (f32x4){bflo(g.z), bfhi(g.z), bflo(g.w), bfhi(g.w)});
;                 }
;             }
	s_nop 1
	v_mov_b64_e32 v[102:103], v[194:195]
	v_mov_b64_e32 v[104:105], v[196:197]
	v_lshlrev_b32_e32 v108, 16, v102
	v_and_b32_e32 v109, 0xffff0000, v102
	v_lshlrev_b32_e32 v102, 16, v103
	v_and_b32_e32 v103, 0xffff0000, v103
	v_lshlrev_b32_e32 v110, 16, v104
	v_and_b32_e32 v111, 0xffff0000, v104
	v_lshlrev_b32_e32 v104, 16, v105
	v_and_b32_e32 v105, 0xffff0000, v105
	v_pk_mul_f32 v[100:101], v[100:101], v[102:103]
	v_pk_mul_f32 v[102:103], v[96:97], v[104:105]
	v_pk_mul_f32 v[96:97], v[94:95], v[110:111]
	v_pk_mul_f32 v[98:99], v[98:99], v[108:109]
	s_nop 0
	v_cvt_pk_bf16_f32 v94, v98, v99
	v_cvt_pk_bf16_f32 v95, v100, v101
	v_cvt_pk_bf16_f32 v96, v96, v97
	v_cvt_pk_bf16_f32 v97, v102, v103
	global_store_dwordx4 v[106:107], v[94:97], off
	v_or_b32_e32 v98, 48, v160
	v_ashrrev_i32_e32 v99, 31, v98
	v_lshlrev_b64 v[98:99], 11, v[98:99]
	v_lshl_add_u64 v[98:99], v[98:99], 0, v[158:159]
	v_lshlrev_b64 v[98:99], 1, v[98:99]
	v_lshl_add_u64 v[100:101], s[54:55], 0, v[98:99]
	s_waitcnt vmcnt(10)
	s_nop 1
	v_mov_b64_e32 v[94:95], v[198:199]
	v_mov_b64_e32 v[96:97], v[200:201]
	v_lshlrev_b32_e32 v102, 16, v94
	v_and_b32_e32 v103, 0xffff0000, v94
	v_lshlrev_b32_e32 v94, 16, v95
	v_and_b32_e32 v95, 0xffff0000, v95
	v_lshlrev_b32_e32 v104, 16, v96
	v_and_b32_e32 v105, 0xffff0000, v96
	v_lshlrev_b32_e32 v96, 16, v97
	v_and_b32_e32 v97, 0xffff0000, v97
	v_pk_mul_f32 v[92:93], v[92:93], v[94:95]
	v_pk_mul_f32 v[94:95], v[88:89], v[96:97]
	v_pk_mul_f32 v[88:89], v[86:87], v[104:105]
	v_pk_mul_f32 v[90:91], v[90:91], v[102:103]
	s_nop 0
	v_cvt_pk_bf16_f32 v86, v90, v91
	v_cvt_pk_bf16_f32 v87, v92, v93
	v_cvt_pk_bf16_f32 v88, v88, v89
	v_cvt_pk_bf16_f32 v89, v94, v95
	global_store_dwordx4 v[106:107], v[86:89], off offset:256
	v_lshl_add_u64 v[90:91], s[30:31], 0, v[98:99]
	s_waitcnt vmcnt(9)
	s_nop 1
	v_mov_b64_e32 v[86:87], v[202:203]
	v_mov_b64_e32 v[88:89], v[204:205]
	v_lshlrev_b32_e32 v92, 16, v86
	v_and_b32_e32 v93, 0xffff0000, v86
	v_lshlrev_b32_e32 v86, 16, v87
	v_and_b32_e32 v87, 0xffff0000, v87
	v_lshlrev_b32_e32 v94, 16, v88
	v_and_b32_e32 v95, 0xffff0000, v88
	v_lshlrev_b32_e32 v88, 16, v89
	v_and_b32_e32 v89, 0xffff0000, v89
	v_pk_mul_f32 v[84:85], v[84:85], v[86:87]
	v_pk_mul_f32 v[86:87], v[80:81], v[88:89]
	v_pk_mul_f32 v[80:81], v[78:79], v[94:95]
	v_pk_mul_f32 v[82:83], v[82:83], v[92:93]
	s_nop 0
	v_cvt_pk_bf16_f32 v78, v82, v83
	v_cvt_pk_bf16_f32 v79, v84, v85
	v_cvt_pk_bf16_f32 v80, v80, v81
	v_cvt_pk_bf16_f32 v81, v86, v87
	global_store_dwordx4 v[90:91], v[78:81], off
	v_lshl_add_u64 v[82:83], v[4:5], 0, s[50:51]
	v_lshl_add_u64 v[84:85], s[54:55], 0, v[82:83]
	s_waitcnt vmcnt(8)
	s_nop 1
	v_mov_b64_e32 v[78:79], v[206:207]
	v_mov_b64_e32 v[80:81], v[208:209]
	v_lshlrev_b32_e32 v86, 16, v78
	v_and_b32_e32 v87, 0xffff0000, v78
	v_lshlrev_b32_e32 v78, 16, v79
	v_and_b32_e32 v79, 0xffff0000, v79
	v_lshlrev_b32_e32 v88, 16, v80
	v_and_b32_e32 v89, 0xffff0000, v80
	v_lshlrev_b32_e32 v80, 16, v81
	v_and_b32_e32 v81, 0xffff0000, v81
	v_pk_mul_f32 v[76:77], v[76:77], v[78:79]
	v_pk_mul_f32 v[78:79], v[72:73], v[80:81]
	v_pk_mul_f32 v[72:73], v[70:71], v[88:89]
	v_pk_mul_f32 v[74:75], v[74:75], v[86:87]
	s_nop 0
	v_cvt_pk_bf16_f32 v70, v74, v75
	v_cvt_pk_bf16_f32 v71, v76, v77
	v_cvt_pk_bf16_f32 v72, v72, v73
	v_cvt_pk_bf16_f32 v73, v78, v79
	global_store_dwordx4 v[90:91], v[70:73], off offset:256
	v_lshl_add_u64 v[74:75], s[30:31], 0, v[82:83]
	s_waitcnt vmcnt(7)
	s_nop 1
	v_mov_b64_e32 v[70:71], v[210:211]
	v_mov_b64_e32 v[72:73], v[212:213]
	v_lshlrev_b32_e32 v76, 16, v70
	v_and_b32_e32 v77, 0xffff0000, v70
	v_lshlrev_b32_e32 v70, 16, v71
	v_and_b32_e32 v71, 0xffff0000, v71
	v_lshlrev_b32_e32 v78, 16, v72
	v_and_b32_e32 v79, 0xffff0000, v72
	v_lshlrev_b32_e32 v72, 16, v73
	v_and_b32_e32 v73, 0xffff0000, v73
	v_pk_mul_f32 v[68:69], v[68:69], v[70:71]
	v_pk_mul_f32 v[70:71], v[64:65], v[72:73]
	v_pk_mul_f32 v[64:65], v[62:63], v[78:79]
	v_pk_mul_f32 v[66:67], v[66:67], v[76:77]
	s_nop 0
	v_cvt_pk_bf16_f32 v62, v66, v67
	v_cvt_pk_bf16_f32 v63, v68, v69
	v_cvt_pk_bf16_f32 v64, v64, v65
	v_cvt_pk_bf16_f32 v65, v70, v71
	global_store_dwordx4 v[74:75], v[62:65], off
	v_lshl_add_u64 v[66:67], v[4:5], 0, s[60:61]
	v_lshl_add_u64 v[68:69], s[54:55], 0, v[66:67]
	s_waitcnt vmcnt(6)
	s_nop 1
	v_mov_b64_e32 v[62:63], v[214:215]
	v_mov_b64_e32 v[64:65], v[216:217]
	v_lshlrev_b32_e32 v70, 16, v62
	v_and_b32_e32 v71, 0xffff0000, v62
	v_lshlrev_b32_e32 v62, 16, v63
	v_and_b32_e32 v63, 0xffff0000, v63
	v_lshlrev_b32_e32 v72, 16, v64
	v_and_b32_e32 v73, 0xffff0000, v64
	v_lshlrev_b32_e32 v64, 16, v65
	v_and_b32_e32 v65, 0xffff0000, v65
	v_pk_mul_f32 v[60:61], v[60:61], v[62:63]
	v_pk_mul_f32 v[62:63], v[56:57], v[64:65]
	v_pk_mul_f32 v[56:57], v[54:55], v[72:73]
	v_pk_mul_f32 v[58:59], v[58:59], v[70:71]
	s_nop 0
	v_cvt_pk_bf16_f32 v54, v58, v59
	v_cvt_pk_bf16_f32 v55, v60, v61
	v_cvt_pk_bf16_f32 v56, v56, v57
	v_cvt_pk_bf16_f32 v57, v62, v63
	global_store_dwordx4 v[74:75], v[54:57], off offset:256
	v_lshl_add_u64 v[58:59], s[30:31], 0, v[66:67]
	s_waitcnt vmcnt(5)
; __device__ __forceinline__ void st8(bf16_t* p, const f32x4& a, const f32x4& b) { u32x4 w; w.x = pk2(a[0], a[1]); w.y = pk2(a[2], a[3]); w.z = pk2(b[0], b[1]); w.w = pk2(b[2], b[3]); *(u32x4*)p = w; }
;     __device__ __forceinline__ void operator()(const f32x4 (&acc)[2][2][4][2], const Unit& u, int wr, int wc, int fr, int fq) const {
;     ...
; #pragma unroll
;         for (int ai = 0; ai < 2; ++ai)
; #pragma unroll
;             for (int m = 0; m < 4; ++m) {
;                 const size_t off = (size_t)(row0 + ai * 128 + m * 16) * D + col0;
; #pragma unroll
;                 for (int bj = 0; bj < 2; ++bj) {
;                     const u32x4 g = *(const u32x4*)(GA + off + bj * 128);
;                     st8(O + off + bj * 128, acc[ai][bj][m][0] * (f32x4){bflo(g.x), bfhi(g.x), bflo(g.y), bfhi(g.y)}, acc[ai][bj][m][1] * (f32x4){bflo(g.z), bfhi(g.z), bflo(g.w), bfhi(g.w)});
;                 }
;             }
	s_nop 1
	v_mov_b64_e32 v[54:55], v[218:219]
	v_mov_b64_e32 v[56:57], v[220:221]
	v_lshlrev_b32_e32 v60, 16, v54
	v_and_b32_e32 v61, 0xffff0000, v54
	v_lshlrev_b32_e32 v54, 16, v55
	v_and_b32_e32 v55, 0xffff0000, v55
	v_lshlrev_b32_e32 v62, 16, v56
	v_and_b32_e32 v63, 0xffff0000, v56
	v_lshlrev_b32_e32 v56, 16, v57
	v_and_b32_e32 v57, 0xffff0000, v57
	v_pk_mul_f32 v[52:53], v[52:53], v[54:55]
	v_pk_mul_f32 v[54:55], v[48:49], v[56:57]
	v_pk_mul_f32 v[48:49], v[46:47], v[62:63]
	v_pk_mul_f32 v[50:51], v[50:51], v[60:61]
	s_nop 0
	v_cvt_pk_bf16_f32 v46, v50, v51
	v_cvt_pk_bf16_f32 v47, v52, v53
	v_cvt_pk_bf16_f32 v48, v48, v49
	v_cvt_pk_bf16_f32 v49, v54, v55
	global_store_dwordx4 v[58:59], v[46:49], off
	v_lshl_add_u64 v[50:51], v[4:5], 0, s[62:63]
	v_lshl_add_u64 v[52:53], s[54:55], 0, v[50:51]
	v_lshl_add_u64 v[4:5], v[4:5], 0, s[64:65]
	s_waitcnt vmcnt(4)
	s_nop 1
	v_mov_b64_e32 v[46:47], v[222:223]
	v_mov_b64_e32 v[48:49], v[224:225]
	v_lshlrev_b32_e32 v54, 16, v46
	v_and_b32_e32 v55, 0xffff0000, v46
	v_lshlrev_b32_e32 v46, 16, v47
	v_and_b32_e32 v47, 0xffff0000, v47
	v_lshlrev_b32_e32 v56, 16, v48
	v_and_b32_e32 v57, 0xffff0000, v48
	v_lshlrev_b32_e32 v48, 16, v49
	v_and_b32_e32 v49, 0xffff0000, v49
	v_pk_mul_f32 v[44:45], v[44:45], v[46:47]
	v_pk_mul_f32 v[46:47], v[40:41], v[48:49]
	v_pk_mul_f32 v[40:41], v[38:39], v[56:57]
	v_pk_mul_f32 v[42:43], v[42:43], v[54:55]
	s_nop 0
	v_cvt_pk_bf16_f32 v38, v42, v43
	v_cvt_pk_bf16_f32 v39, v44, v45
	v_cvt_pk_bf16_f32 v40, v40, v41
	v_cvt_pk_bf16_f32 v41, v46, v47
	global_store_dwordx4 v[58:59], v[38:41], off offset:256
	v_lshl_add_u64 v[42:43], s[30:31], 0, v[50:51]
	s_waitcnt vmcnt(3)
	s_nop 1
	v_mov_b64_e32 v[38:39], v[226:227]
	v_mov_b64_e32 v[40:41], v[228:229]
	v_lshlrev_b32_e32 v44, 16, v38
	v_and_b32_e32 v45, 0xffff0000, v38
	v_lshlrev_b32_e32 v38, 16, v39
	v_and_b32_e32 v39, 0xffff0000, v39
	v_lshlrev_b32_e32 v46, 16, v40
	v_and_b32_e32 v47, 0xffff0000, v40
	v_lshlrev_b32_e32 v40, 16, v41
	v_and_b32_e32 v41, 0xffff0000, v41
	v_pk_mul_f32 v[36:37], v[36:37], v[38:39]
	v_pk_mul_f32 v[38:39], v[32:33], v[40:41]
	v_pk_mul_f32 v[32:33], v[30:31], v[46:47]
	v_pk_mul_f32 v[34:35], v[34:35], v[44:45]
	s_nop 0
	v_cvt_pk_bf16_f32 v30, v34, v35
	v_cvt_pk_bf16_f32 v31, v36, v37
	v_cvt_pk_bf16_f32 v32, v32, v33
	v_cvt_pk_bf16_f32 v33, v38, v39
	global_store_dwordx4 v[42:43], v[30:33], off
	v_lshl_add_u64 v[34:35], s[54:55], 0, v[4:5]
	s_waitcnt vmcnt(2)
	s_nop 1
	v_mov_b64_e32 v[30:31], v[230:231]
	v_mov_b64_e32 v[32:33], v[232:233]
	v_lshlrev_b32_e32 v36, 16, v30
	v_and_b32_e32 v37, 0xffff0000, v30
	v_lshlrev_b32_e32 v30, 16, v31
	v_and_b32_e32 v31, 0xffff0000, v31
	v_lshlrev_b32_e32 v38, 16, v32
	v_and_b32_e32 v39, 0xffff0000, v32
	v_lshlrev_b32_e32 v32, 16, v33
	v_and_b32_e32 v33, 0xffff0000, v33
	v_pk_mul_f32 v[28:29], v[28:29], v[30:31]
	v_pk_mul_f32 v[30:31], v[24:25], v[32:33]
	v_pk_mul_f32 v[24:25], v[22:23], v[38:39]
	v_pk_mul_f32 v[26:27], v[26:27], v[36:37]
	s_nop 0
	v_cvt_pk_bf16_f32 v22, v26, v27
	v_cvt_pk_bf16_f32 v23, v28, v29
	v_cvt_pk_bf16_f32 v24, v24, v25
	v_cvt_pk_bf16_f32 v25, v30, v31
	global_store_dwordx4 v[42:43], v[22:25], off offset:256
	v_lshl_add_u64 v[26:27], s[30:31], 0, v[4:5]
	s_waitcnt vmcnt(1)
	s_nop 1
	v_mov_b64_e32 v[22:23], v[234:235]
	v_mov_b64_e32 v[24:25], v[236:237]
	v_lshlrev_b32_e32 v4, 16, v22
	v_and_b32_e32 v5, 0xffff0000, v22
	v_lshlrev_b32_e32 v28, 16, v24
	v_and_b32_e32 v29, 0xffff0000, v24
	v_lshlrev_b32_e32 v24, 16, v25
	v_and_b32_e32 v25, 0xffff0000, v25
	v_lshlrev_b32_e32 v22, 16, v23
	v_and_b32_e32 v23, 0xffff0000, v23
	v_pk_mul_f32 v[4:5], v[18:19], v[4:5]
	v_pk_mul_f32 v[18:19], v[16:17], v[24:25]
	v_pk_mul_f32 v[16:17], v[14:15], v[28:29]
	v_pk_mul_f32 v[20:21], v[20:21], v[22:23]
	v_cvt_pk_bf16_f32 v14, v4, v5
	s_nop 0
	v_cvt_pk_bf16_f32 v15, v20, v21
	v_cvt_pk_bf16_f32 v16, v16, v17
	v_cvt_pk_bf16_f32 v17, v18, v19
	global_store_dwordx4 v[26:27], v[14:17], off
	s_waitcnt vmcnt(0)
	s_nop 1
	v_mov_b64_e32 v[14:15], v[238:239]
	v_mov_b64_e32 v[16:17], v[240:241]
	v_lshlrev_b32_e32 v4, 16, v14
	v_and_b32_e32 v5, 0xffff0000, v14
	v_lshlrev_b32_e32 v18, 16, v16
	v_and_b32_e32 v19, 0xffff0000, v16
	v_lshlrev_b32_e32 v14, 16, v15
	v_and_b32_e32 v15, 0xffff0000, v15
	v_lshlrev_b32_e32 v16, 16, v17
	v_and_b32_e32 v17, 0xffff0000, v17
	v_pk_mul_f32 v[4:5], v[10:11], v[4:5]
	v_pk_mul_f32 v[6:7], v[6:7], v[18:19]
	v_pk_mul_f32 v[12:13], v[12:13], v[14:15]
	v_pk_mul_f32 v[8:9], v[8:9], v[16:17]
	v_cvt_pk_bf16_f32 v4, v4, v5
	v_cvt_pk_bf16_f32 v5, v12, v13
	v_cvt_pk_bf16_f32 v6, v6, v7
	s_nop 0
	v_cvt_pk_bf16_f32 v7, v8, v9
	global_store_dwordx4 v[26:27], v[4:7], off offset:256
	s_cbranch_vccnz .LBB0_556
	s_andn2_b64 vcc, exec, s[52:53]
	s_cbranch_vccnz .LBB0_555
	s_barrier
	s_branch .LBB0_555
